# v89 + residual-GEMM epilogues: residual tiles of all chunks loaded up front into free fragment registers with counted waits (one exposed latency per tile)
# speedup vs baseline: 1.0029x; 1.0029x over previous
.LBB0_1088:
	s_lshl_b32 s0, s5, 8
	v_mov_b32_e32 v32, v155
	v_mov_b32_e32 v130, v154
	s_add_i32 s0, s0, s93
	s_lshl_b32 s82, s4, 2
	v_add_u32_e32 v150, s0, v32
	s_lshl_b32 s0, s4, 9
	s_or_b32 s0, s0, s94
	v_lshlrev_b32_e32 v32, 11, v150
	v_lshlrev_b32_e32 v131, 4, v130
	v_add3_u32 v158, s0, v131, v32
	global_load_dwordx4 v[160:163], v158, s[52:53]
	v_add_u32_e32 v151, 0x100, v158
	global_load_dwordx4 v[164:167], v151, s[52:53]
	v_add_u32_e32 v32, 0x8000, v158
	v_add_u32_e32 v152, 0x8100, v158
	v_cmp_eq_u32_e32 vcc, 0, v130
	global_load_dwordx4 v[134:137], v32, s[52:53]
	global_load_dwordx4 v[130:133], v152, s[52:53]
	v_add_u32_e32 v168, 0x10000, v158
	global_load_dwordx4 v[172:175], v168, s[52:53]
	v_add_u32_e32 v169, 0x10100, v158
	global_load_dwordx4 v[176:179], v169, s[52:53]
	v_add_u32_e32 v168, 0x18000, v158
	global_load_dwordx4 v[180:183], v168, s[52:53]
	v_add_u32_e32 v169, 0x18100, v158
	global_load_dwordx4 v[186:189], v169, s[52:53]
	v_add_u32_e32 v168, 0x40000, v158
	global_load_dwordx4 v[190:193], v168, s[52:53]
	v_add_u32_e32 v169, 0x40100, v158
	global_load_dwordx4 v[202:205], v169, s[52:53]
	v_add_u32_e32 v168, 0x48000, v158
	global_load_dwordx4 v[206:209], v168, s[52:53]
	v_add_u32_e32 v169, 0x48100, v158
	global_load_dwordx4 v[210:213], v169, s[52:53]
	v_add_u32_e32 v168, 0x50000, v158
	global_load_dwordx4 v[214:217], v168, s[52:53]
	v_add_u32_e32 v169, 0x50100, v158
	global_load_dwordx4 v[218:221], v169, s[52:53]
	s_ashr_i32 s83, s82, 31
	s_waitcnt vmcnt(12)
	v_lshlrev_b32_e32 v168, 16, v160
	v_and_b32_e32 v169, 0xffff0000, v160
	v_lshlrev_b32_e32 v160, 16, v161
	v_and_b32_e32 v161, 0xffff0000, v161
	v_lshlrev_b32_e32 v170, 16, v162
	v_and_b32_e32 v171, 0xffff0000, v162
	v_lshlrev_b32_e32 v162, 16, v163
	v_and_b32_e32 v163, 0xffff0000, v163
	v_pk_add_f32 v[128:129], v[128:129], v[160:161]
	v_pk_add_f32 v[126:127], v[126:127], v[168:169]
	v_pk_add_f32 v[160:161], v[124:125], v[162:163]
	v_pk_add_f32 v[162:163], v[122:123], v[170:171]
	v_cvt_pk_bf16_f32 v122, v126, v127
	v_cvt_pk_bf16_f32 v123, v128, v129
	s_nop 0
	v_cvt_pk_bf16_f32 v124, v162, v163
	v_cvt_pk_bf16_f32 v125, v160, v161
	global_store_dwordx4 v158, v[122:125], s[52:53]
	s_nop 1
	v_mul_f32_e32 v122, v127, v127
	v_mul_f32_e32 v123, v129, v129
	v_fmac_f32_e32 v122, v126, v126
	v_fmac_f32_e32 v123, v128, v128
	v_add_f32_e32 v122, v122, v123
	v_mul_f32_e32 v123, v163, v163
	v_fmac_f32_e32 v123, v162, v162
	v_add_f32_e32 v122, v123, v122
	v_mul_f32_e32 v123, v161, v161
	v_fmac_f32_e32 v123, v160, v160
	v_add_f32_e32 v153, v123, v122
	v_lshlrev_b32_e32 v122, 16, v164
	v_and_b32_e32 v123, 0xffff0000, v164
	v_lshlrev_b32_e32 v124, 16, v165
	v_and_b32_e32 v125, 0xffff0000, v165
	v_lshlrev_b32_e32 v126, 16, v166
	v_and_b32_e32 v127, 0xffff0000, v166
	v_lshlrev_b32_e32 v128, 16, v167
	v_and_b32_e32 v129, 0xffff0000, v167
	v_pk_add_f32 v[120:121], v[120:121], v[124:125]
	v_pk_add_f32 v[118:119], v[118:119], v[122:123]
	v_pk_add_f32 v[124:125], v[114:115], v[126:127]
	v_cvt_pk_bf16_f32 v114, v118, v119
	v_cvt_pk_bf16_f32 v115, v120, v121
	v_pk_add_f32 v[122:123], v[116:117], v[128:129]
	v_cvt_pk_bf16_f32 v116, v124, v125
	s_nop 0
	v_cvt_pk_bf16_f32 v117, v122, v123
	global_store_dwordx4 v151, v[114:117], s[52:53]
	s_nop 1
	v_mul_f32_e32 v114, v119, v119
	v_mul_f32_e32 v115, v121, v121
	v_fmac_f32_e32 v114, v118, v118
	v_fmac_f32_e32 v115, v120, v120
	v_add_f32_e32 v114, v114, v115
	v_mul_f32_e32 v115, v125, v125
	v_fmac_f32_e32 v115, v124, v124
	v_add_f32_e32 v114, v115, v114
	v_mul_f32_e32 v115, v123, v123
	v_fmac_f32_e32 v115, v122, v122
	v_and_b32_e32 v116, 64, v238
	v_add_f32_e32 v114, v115, v114
	v_xor_b32_e32 v115, 16, v238
	v_add_u32_e32 v116, 64, v116
	v_cmp_lt_i32_e64 s[0:1], v115, v116
	v_add_f32_e32 v114, v153, v114
	s_nop 0
	v_cndmask_b32_e64 v115, v238, v115, s[0:1]
	v_lshlrev_b32_e32 v124, 2, v115
	v_mov_b32_e32 v115, v114
	s_nop 1
	v_permlane16_swap_b32 v115, v114
	s_waitcnt lgkmcnt(0)
	v_add_f32_e32 v114, v114, v115
	v_xor_b32_e32 v115, 32, v238
	v_cmp_lt_i32_e64 s[0:1], v115, v116
	s_nop 1
	v_cndmask_b32_e64 v115, v238, v115, s[0:1]
	v_lshlrev_b32_e32 v125, 2, v115
	v_mov_b32_e32 v115, v114
	s_nop 1
	v_permlane32_swap_b32 v115, v114
	s_and_saveexec_b64 s[0:1], vcc
	s_cbranch_execz .LBB0_1090
	v_ashrrev_i32_e32 v151, 31, v150
	s_waitcnt lgkmcnt(0)
	v_add_f32_e32 v116, v114, v115
	v_lshlrev_b64 v[114:115], 6, v[150:151]
	v_lshl_add_u64 v[114:115], s[54:55], 0, v[114:115]
	v_lshl_add_u64 v[114:115], s[82:83], 2, v[114:115]
	s_lshl_b32 s16, s88, 2
	v_lshl_add_u64 v[114:115], v[114:115], 0, s[16:17]
	global_store_dword v[114:115], v116, off
.LBB0_1090:
	s_or_b64 exec, exec, s[0:1]
	v_lshl_add_u64 v[126:127], s[52:53], 0, v[32:33]
	v_add_u32_e32 v32, 0x10000, v158
	v_add_u32_e32 v122, 0x10100, v158
	s_waitcnt vmcnt(13)
	s_waitcnt lgkmcnt(0)
	v_mov_b32_e32 v153, v33
	v_lshl_add_u64 v[128:129], s[52:53], 0, v[152:153]
	v_lshlrev_b32_e32 v152, 16, v134
	v_and_b32_e32 v153, 0xffff0000, v134
	v_lshlrev_b32_e32 v134, 16, v135
	v_and_b32_e32 v135, 0xffff0000, v135
	v_lshlrev_b32_e32 v160, 16, v136
	v_and_b32_e32 v161, 0xffff0000, v136
	v_lshlrev_b32_e32 v136, 16, v137
	v_and_b32_e32 v137, 0xffff0000, v137
	v_pk_add_f32 v[110:111], v[110:111], v[152:153]
	v_pk_add_f32 v[112:113], v[112:113], v[134:135]
	v_pk_add_f32 v[134:135], v[108:109], v[136:137]
	v_pk_add_f32 v[108:109], v[106:107], v[160:161]
	v_cvt_pk_bf16_f32 v106, v110, v111
	v_mul_f32_e32 v111, v111, v111
	v_fmac_f32_e32 v111, v110, v110
	v_mul_f32_e32 v110, v113, v113
	v_fmac_f32_e32 v110, v112, v112
	v_add_f32_e32 v110, v111, v110
	v_mul_f32_e32 v111, v109, v109
	v_fmac_f32_e32 v111, v108, v108
	v_add_f32_e32 v110, v111, v110
	v_mul_f32_e32 v111, v135, v135
	v_fmac_f32_e32 v111, v134, v134
	v_cvt_pk_bf16_f32 v107, v112, v113
	v_add_f32_e32 v123, v111, v110
	v_lshlrev_b32_e32 v110, 16, v130
	v_and_b32_e32 v111, 0xffff0000, v130
	v_lshlrev_b32_e32 v112, 16, v131
	v_and_b32_e32 v113, 0xffff0000, v131
	v_lshlrev_b32_e32 v130, 16, v132
	v_and_b32_e32 v131, 0xffff0000, v132
	v_pk_add_f32 v[104:105], v[104:105], v[112:113]
	v_pk_add_f32 v[102:103], v[102:103], v[110:111]
	v_pk_add_f32 v[112:113], v[98:99], v[130:131]
	v_mul_f32_e32 v98, v103, v103
	v_mul_f32_e32 v99, v105, v105
	v_fmac_f32_e32 v98, v102, v102
	v_fmac_f32_e32 v99, v104, v104
	v_lshlrev_b32_e32 v132, 16, v133
	v_and_b32_e32 v133, 0xffff0000, v133
	v_add_f32_e32 v98, v98, v99
	v_mul_f32_e32 v99, v113, v113
	v_pk_add_f32 v[110:111], v[100:101], v[132:133]
	v_fmac_f32_e32 v99, v112, v112
	v_add_f32_e32 v98, v99, v98
	v_mul_f32_e32 v99, v111, v111
	v_fmac_f32_e32 v99, v110, v110
	v_add_f32_e32 v98, v99, v98
	v_add_f32_e32 v98, v123, v98
	v_mov_b32_e32 v99, v98
	s_nop 1
	v_permlane16_swap_b32 v99, v98
	v_cvt_pk_bf16_f32 v108, v108, v109
	v_cvt_pk_bf16_f32 v109, v134, v135
	global_store_dwordx4 v[126:127], v[106:109], off
	v_cvt_pk_bf16_f32 v100, v102, v103
	s_waitcnt lgkmcnt(0)
	v_add_f32_e32 v98, v98, v99
	v_mov_b32_e32 v99, v98
	s_nop 1
	v_permlane32_swap_b32 v99, v98
	v_cvt_pk_bf16_f32 v101, v104, v105
	v_cvt_pk_bf16_f32 v102, v112, v113
	v_cvt_pk_bf16_f32 v103, v110, v111
	global_store_dwordx4 v[128:129], v[100:103], off
	s_and_saveexec_b64 s[0:1], vcc
	s_cbranch_execz .LBB0_1092
	v_add_u32_e32 v100, 16, v150
	v_ashrrev_i32_e32 v101, 31, v100
	s_waitcnt lgkmcnt(0)
	v_add_f32_e32 v102, v98, v99
	v_lshlrev_b64 v[98:99], 6, v[100:101]
	v_lshl_add_u64 v[98:99], s[54:55], 0, v[98:99]
	v_lshl_add_u64 v[98:99], s[82:83], 2, v[98:99]
	s_lshl_b32 s16, s88, 2
	v_lshl_add_u64 v[98:99], v[98:99], 0, s[16:17]
	global_store_dword v[98:99], v102, off
.LBB0_1092:
	s_or_b64 exec, exec, s[0:1]
	v_lshl_add_u64 v[108:109], s[52:53], 0, v[32:33]
	v_add_u32_e32 v32, 0x18000, v158
	v_add_u32_e32 v106, 0x18100, v158
	v_add_u32_e32 v168, 0x58000, v158
	global_load_dwordx4 v[134:137], v168, s[52:53]
	v_add_u32_e32 v169, 0x58100, v158
	global_load_dwordx4 v[130:133], v169, s[52:53]
	s_waitcnt lgkmcnt(0)
	v_mov_b32_e32 v123, v33
	s_waitcnt vmcnt(16)
	v_lshlrev_b32_e32 v112, 16, v172
	v_and_b32_e32 v113, 0xffff0000, v172
	v_lshl_add_u64 v[110:111], s[52:53], 0, v[122:123]
	v_lshlrev_b32_e32 v118, 16, v173
	v_and_b32_e32 v119, 0xffff0000, v173
	v_lshlrev_b32_e32 v122, 16, v174
	v_and_b32_e32 v123, 0xffff0000, v174
	v_lshlrev_b32_e32 v120, 16, v175
	v_and_b32_e32 v121, 0xffff0000, v175
	v_pk_add_f32 v[94:95], v[94:95], v[112:113]
	v_pk_add_f32 v[96:97], v[96:97], v[118:119]
	v_pk_add_f32 v[112:113], v[92:93], v[120:121]
	v_pk_add_f32 v[92:93], v[90:91], v[122:123]
	v_cvt_pk_bf16_f32 v90, v94, v95
	v_mul_f32_e32 v95, v95, v95
	v_fmac_f32_e32 v95, v94, v94
	v_mul_f32_e32 v94, v97, v97
	v_fmac_f32_e32 v94, v96, v96
	v_add_f32_e32 v94, v95, v94
	v_mul_f32_e32 v95, v93, v93
	v_fmac_f32_e32 v95, v92, v92
	v_add_f32_e32 v94, v95, v94
	v_mul_f32_e32 v95, v113, v113
	v_fmac_f32_e32 v95, v112, v112
	v_cvt_pk_bf16_f32 v91, v96, v97
	v_add_f32_e32 v107, v95, v94
	v_lshlrev_b32_e32 v94, 16, v176
	v_and_b32_e32 v95, 0xffff0000, v176
	v_lshlrev_b32_e32 v96, 16, v177
	v_and_b32_e32 v97, 0xffff0000, v177
	v_lshlrev_b32_e32 v114, 16, v178
	v_and_b32_e32 v115, 0xffff0000, v178
	v_pk_add_f32 v[88:89], v[88:89], v[96:97]
	v_pk_add_f32 v[86:87], v[86:87], v[94:95]
	v_pk_add_f32 v[96:97], v[82:83], v[114:115]
	v_mul_f32_e32 v82, v87, v87
	v_mul_f32_e32 v83, v89, v89
	v_fmac_f32_e32 v82, v86, v86
	v_fmac_f32_e32 v83, v88, v88
	v_lshlrev_b32_e32 v116, 16, v179
	v_and_b32_e32 v117, 0xffff0000, v179
	v_add_f32_e32 v82, v82, v83
	v_mul_f32_e32 v83, v97, v97
	v_pk_add_f32 v[94:95], v[84:85], v[116:117]
	v_fmac_f32_e32 v83, v96, v96
	v_add_f32_e32 v82, v83, v82
	v_mul_f32_e32 v83, v95, v95
	v_fmac_f32_e32 v83, v94, v94
	v_add_f32_e32 v82, v83, v82
	v_add_f32_e32 v82, v107, v82
	v_mov_b32_e32 v83, v82
	s_nop 1
	v_permlane16_swap_b32 v83, v82
	v_cvt_pk_bf16_f32 v92, v92, v93
	v_cvt_pk_bf16_f32 v93, v112, v113
	global_store_dwordx4 v[108:109], v[90:93], off
	v_cvt_pk_bf16_f32 v84, v86, v87
	s_waitcnt lgkmcnt(0)
	v_add_f32_e32 v82, v82, v83
	v_mov_b32_e32 v83, v82
	s_nop 1
	v_permlane32_swap_b32 v83, v82
	v_cvt_pk_bf16_f32 v85, v88, v89
	v_cvt_pk_bf16_f32 v86, v96, v97
	v_cvt_pk_bf16_f32 v87, v94, v95
	global_store_dwordx4 v[110:111], v[84:87], off
	s_and_saveexec_b64 s[0:1], vcc
	s_cbranch_execz .LBB0_1094
	v_add_u32_e32 v84, 32, v150
	v_ashrrev_i32_e32 v85, 31, v84
	s_waitcnt lgkmcnt(0)
	v_add_f32_e32 v86, v82, v83
	v_lshlrev_b64 v[82:83], 6, v[84:85]
	v_lshl_add_u64 v[82:83], s[54:55], 0, v[82:83]
	v_lshl_add_u64 v[82:83], s[82:83], 2, v[82:83]
	s_lshl_b32 s16, s88, 2
	v_lshl_add_u64 v[82:83], v[82:83], 0, s[16:17]
	global_store_dword v[82:83], v86, off
.LBB0_1094:
	s_or_b64 exec, exec, s[0:1]
	v_lshl_add_u64 v[92:93], s[52:53], 0, v[32:33]
	v_add_u32_e32 v32, 0x40000, v158
	v_add_u32_e32 v90, 0x40100, v158
	s_waitcnt lgkmcnt(0)
	v_mov_b32_e32 v107, v33
	s_waitcnt vmcnt(17)
	v_lshlrev_b32_e32 v96, 16, v180
	v_and_b32_e32 v97, 0xffff0000, v180
	v_lshl_add_u64 v[94:95], s[52:53], 0, v[106:107]
	v_lshlrev_b32_e32 v102, 16, v181
	v_and_b32_e32 v103, 0xffff0000, v181
	v_lshlrev_b32_e32 v106, 16, v182
	v_and_b32_e32 v107, 0xffff0000, v182
	v_lshlrev_b32_e32 v104, 16, v183
	v_and_b32_e32 v105, 0xffff0000, v183
	v_pk_add_f32 v[78:79], v[78:79], v[96:97]
	v_pk_add_f32 v[80:81], v[80:81], v[102:103]
	v_pk_add_f32 v[96:97], v[76:77], v[104:105]
	v_pk_add_f32 v[76:77], v[74:75], v[106:107]
	v_cvt_pk_bf16_f32 v74, v78, v79
	v_mul_f32_e32 v79, v79, v79
	v_fmac_f32_e32 v79, v78, v78
	v_mul_f32_e32 v78, v81, v81
	v_fmac_f32_e32 v78, v80, v80
	v_add_f32_e32 v78, v79, v78
	v_mul_f32_e32 v79, v77, v77
	v_fmac_f32_e32 v79, v76, v76
	v_add_f32_e32 v78, v79, v78
	v_mul_f32_e32 v79, v97, v97
	v_fmac_f32_e32 v79, v96, v96
	v_cvt_pk_bf16_f32 v75, v80, v81
	v_add_f32_e32 v91, v79, v78
	v_lshlrev_b32_e32 v78, 16, v186
	v_and_b32_e32 v79, 0xffff0000, v186
	v_lshlrev_b32_e32 v80, 16, v187
	v_and_b32_e32 v81, 0xffff0000, v187
	v_lshlrev_b32_e32 v98, 16, v188
	v_and_b32_e32 v99, 0xffff0000, v188
	v_pk_add_f32 v[72:73], v[72:73], v[80:81]
	v_pk_add_f32 v[70:71], v[70:71], v[78:79]
	v_pk_add_f32 v[80:81], v[66:67], v[98:99]
	v_mul_f32_e32 v66, v71, v71
	v_mul_f32_e32 v67, v73, v73
	v_fmac_f32_e32 v66, v70, v70
	v_fmac_f32_e32 v67, v72, v72
	v_lshlrev_b32_e32 v100, 16, v189
	v_and_b32_e32 v101, 0xffff0000, v189
	v_add_f32_e32 v66, v66, v67
	v_mul_f32_e32 v67, v81, v81
	v_pk_add_f32 v[78:79], v[68:69], v[100:101]
	v_fmac_f32_e32 v67, v80, v80
	v_add_f32_e32 v66, v67, v66
	v_mul_f32_e32 v67, v79, v79
	v_fmac_f32_e32 v67, v78, v78
	v_add_f32_e32 v66, v67, v66
	v_add_f32_e32 v66, v91, v66
	v_mov_b32_e32 v67, v66
	s_nop 1
	v_permlane16_swap_b32 v67, v66
	v_cvt_pk_bf16_f32 v76, v76, v77
	v_cvt_pk_bf16_f32 v77, v96, v97
	global_store_dwordx4 v[92:93], v[74:77], off
	v_cvt_pk_bf16_f32 v68, v70, v71
	s_waitcnt lgkmcnt(0)
	v_add_f32_e32 v66, v66, v67
	v_mov_b32_e32 v67, v66
	s_nop 1
	v_permlane32_swap_b32 v67, v66
	v_cvt_pk_bf16_f32 v69, v72, v73
	v_cvt_pk_bf16_f32 v70, v80, v81
	v_cvt_pk_bf16_f32 v71, v78, v79
	global_store_dwordx4 v[94:95], v[68:71], off
	s_and_saveexec_b64 s[0:1], vcc
	s_cbranch_execz .LBB0_1096
	v_add_u32_e32 v68, 48, v150
	v_ashrrev_i32_e32 v69, 31, v68
	s_waitcnt lgkmcnt(0)
	v_add_f32_e32 v70, v66, v67
	v_lshlrev_b64 v[66:67], 6, v[68:69]
	v_lshl_add_u64 v[66:67], s[54:55], 0, v[66:67]
	v_lshl_add_u64 v[66:67], s[82:83], 2, v[66:67]
	s_lshl_b32 s16, s88, 2
	v_lshl_add_u64 v[66:67], v[66:67], 0, s[16:17]
	global_store_dword v[66:67], v70, off
.LBB0_1096:
	s_or_b64 exec, exec, s[0:1]
	v_lshl_add_u64 v[76:77], s[52:53], 0, v[32:33]
	v_add_u32_e32 v32, 0x48000, v158
	v_add_u32_e32 v74, 0x48100, v158
	s_waitcnt lgkmcnt(0)
	v_mov_b32_e32 v91, v33
	s_waitcnt vmcnt(18)
	v_lshlrev_b32_e32 v80, 16, v190
	v_and_b32_e32 v81, 0xffff0000, v190
	v_lshl_add_u64 v[78:79], s[52:53], 0, v[90:91]
	v_lshlrev_b32_e32 v86, 16, v191
	v_and_b32_e32 v87, 0xffff0000, v191
	v_lshlrev_b32_e32 v90, 16, v192
	v_and_b32_e32 v91, 0xffff0000, v192
	v_lshlrev_b32_e32 v88, 16, v193
	v_and_b32_e32 v89, 0xffff0000, v193
	v_pk_add_f32 v[62:63], v[62:63], v[80:81]
	v_pk_add_f32 v[64:65], v[64:65], v[86:87]
	v_pk_add_f32 v[80:81], v[60:61], v[88:89]
	v_pk_add_f32 v[60:61], v[58:59], v[90:91]
	v_cvt_pk_bf16_f32 v58, v62, v63
	v_mul_f32_e32 v63, v63, v63
	v_fmac_f32_e32 v63, v62, v62
	v_mul_f32_e32 v62, v65, v65
	v_fmac_f32_e32 v62, v64, v64
	v_add_f32_e32 v62, v63, v62
	v_mul_f32_e32 v63, v61, v61
	v_fmac_f32_e32 v63, v60, v60
	v_add_f32_e32 v62, v63, v62
	v_mul_f32_e32 v63, v81, v81
	v_fmac_f32_e32 v63, v80, v80
	v_cvt_pk_bf16_f32 v59, v64, v65
	v_add_f32_e32 v75, v63, v62
	v_lshlrev_b32_e32 v62, 16, v202
	v_and_b32_e32 v63, 0xffff0000, v202
	v_lshlrev_b32_e32 v64, 16, v203
	v_and_b32_e32 v65, 0xffff0000, v203
	v_lshlrev_b32_e32 v82, 16, v204
	v_and_b32_e32 v83, 0xffff0000, v204
	v_pk_add_f32 v[56:57], v[56:57], v[64:65]
	v_pk_add_f32 v[54:55], v[54:55], v[62:63]
	v_pk_add_f32 v[64:65], v[50:51], v[82:83]
	v_mul_f32_e32 v50, v55, v55
	v_mul_f32_e32 v51, v57, v57
	v_fmac_f32_e32 v50, v54, v54
	v_fmac_f32_e32 v51, v56, v56
	v_lshlrev_b32_e32 v84, 16, v205
	v_and_b32_e32 v85, 0xffff0000, v205
	v_add_f32_e32 v50, v50, v51
	v_mul_f32_e32 v51, v65, v65
	v_pk_add_f32 v[62:63], v[52:53], v[84:85]
	v_fmac_f32_e32 v51, v64, v64
	v_add_f32_e32 v50, v51, v50
	v_mul_f32_e32 v51, v63, v63
	v_fmac_f32_e32 v51, v62, v62
	v_add_f32_e32 v50, v51, v50
	v_add_f32_e32 v50, v75, v50
	v_mov_b32_e32 v51, v50
	s_nop 1
	v_permlane16_swap_b32 v51, v50
	v_cvt_pk_bf16_f32 v60, v60, v61
	v_cvt_pk_bf16_f32 v61, v80, v81
	global_store_dwordx4 v[76:77], v[58:61], off
	v_cvt_pk_bf16_f32 v52, v54, v55
	s_waitcnt lgkmcnt(0)
	v_add_f32_e32 v50, v50, v51
	v_mov_b32_e32 v51, v50
	s_nop 1
	v_permlane32_swap_b32 v51, v50
	v_cvt_pk_bf16_f32 v53, v56, v57
	v_cvt_pk_bf16_f32 v54, v64, v65
	v_cvt_pk_bf16_f32 v55, v62, v63
	global_store_dwordx4 v[78:79], v[52:55], off
	s_and_saveexec_b64 s[0:1], vcc
	s_cbranch_execz .LBB0_1098
	v_add_u32_e32 v52, 0x80, v150
	v_ashrrev_i32_e32 v53, 31, v52
	s_waitcnt lgkmcnt(0)
	v_add_f32_e32 v54, v50, v51
	v_lshlrev_b64 v[50:51], 6, v[52:53]
	v_lshl_add_u64 v[50:51], s[54:55], 0, v[50:51]
	v_lshl_add_u64 v[50:51], s[82:83], 2, v[50:51]
	s_lshl_b32 s16, s88, 2
	v_lshl_add_u64 v[50:51], v[50:51], 0, s[16:17]
	global_store_dword v[50:51], v54, off
.LBB0_1098:
	s_or_b64 exec, exec, s[0:1]
	v_lshl_add_u64 v[60:61], s[52:53], 0, v[32:33]
	v_add_u32_e32 v32, 0x50000, v158
	v_add_u32_e32 v58, 0x50100, v158
	s_waitcnt lgkmcnt(0)
	v_mov_b32_e32 v75, v33
	s_waitcnt vmcnt(19)
	v_lshlrev_b32_e32 v64, 16, v206
	v_and_b32_e32 v65, 0xffff0000, v206
	v_lshl_add_u64 v[62:63], s[52:53], 0, v[74:75]
	v_lshlrev_b32_e32 v70, 16, v207
	v_and_b32_e32 v71, 0xffff0000, v207
	v_lshlrev_b32_e32 v74, 16, v208
	v_and_b32_e32 v75, 0xffff0000, v208
	v_lshlrev_b32_e32 v72, 16, v209
	v_and_b32_e32 v73, 0xffff0000, v209
	v_pk_add_f32 v[46:47], v[46:47], v[64:65]
	v_pk_add_f32 v[48:49], v[48:49], v[70:71]
	v_pk_add_f32 v[64:65], v[44:45], v[72:73]
	v_pk_add_f32 v[44:45], v[42:43], v[74:75]
	v_cvt_pk_bf16_f32 v42, v46, v47
	v_mul_f32_e32 v47, v47, v47
	v_fmac_f32_e32 v47, v46, v46
	v_mul_f32_e32 v46, v49, v49
	v_fmac_f32_e32 v46, v48, v48
	v_add_f32_e32 v46, v47, v46
	v_mul_f32_e32 v47, v45, v45
	v_fmac_f32_e32 v47, v44, v44
	v_add_f32_e32 v46, v47, v46
	v_mul_f32_e32 v47, v65, v65
	v_fmac_f32_e32 v47, v64, v64
	v_cvt_pk_bf16_f32 v43, v48, v49
	v_add_f32_e32 v59, v47, v46
	v_lshlrev_b32_e32 v46, 16, v210
	v_and_b32_e32 v47, 0xffff0000, v210
	v_lshlrev_b32_e32 v48, 16, v211
	v_and_b32_e32 v49, 0xffff0000, v211
	v_lshlrev_b32_e32 v66, 16, v212
	v_and_b32_e32 v67, 0xffff0000, v212
	v_pk_add_f32 v[40:41], v[40:41], v[48:49]
	v_pk_add_f32 v[38:39], v[38:39], v[46:47]
	v_pk_add_f32 v[48:49], v[34:35], v[66:67]
	v_mul_f32_e32 v34, v39, v39
	v_mul_f32_e32 v35, v41, v41
	v_fmac_f32_e32 v34, v38, v38
	v_fmac_f32_e32 v35, v40, v40
	v_lshlrev_b32_e32 v68, 16, v213
	v_and_b32_e32 v69, 0xffff0000, v213
	v_add_f32_e32 v34, v34, v35
	v_mul_f32_e32 v35, v49, v49
	v_pk_add_f32 v[46:47], v[36:37], v[68:69]
	v_fmac_f32_e32 v35, v48, v48
	v_add_f32_e32 v34, v35, v34
	v_mul_f32_e32 v35, v47, v47
	v_fmac_f32_e32 v35, v46, v46
	v_add_f32_e32 v34, v35, v34
	v_add_f32_e32 v34, v59, v34
	v_mov_b32_e32 v35, v34
	s_nop 1
	v_permlane16_swap_b32 v35, v34
	v_cvt_pk_bf16_f32 v44, v44, v45
	v_cvt_pk_bf16_f32 v45, v64, v65
	global_store_dwordx4 v[60:61], v[42:45], off
	v_cvt_pk_bf16_f32 v36, v38, v39
	s_waitcnt lgkmcnt(0)
	v_add_f32_e32 v34, v34, v35
	v_mov_b32_e32 v35, v34
	s_nop 1
	v_permlane32_swap_b32 v35, v34
	v_cvt_pk_bf16_f32 v37, v40, v41
	v_cvt_pk_bf16_f32 v38, v48, v49
	v_cvt_pk_bf16_f32 v39, v46, v47
	global_store_dwordx4 v[62:63], v[36:39], off
	s_and_saveexec_b64 s[0:1], vcc
	s_cbranch_execz .LBB0_1100
	v_add_u32_e32 v36, 0x90, v150
	v_ashrrev_i32_e32 v37, 31, v36
	s_waitcnt lgkmcnt(0)
	v_add_f32_e32 v38, v34, v35
	v_lshlrev_b64 v[34:35], 6, v[36:37]
	v_lshl_add_u64 v[34:35], s[54:55], 0, v[34:35]
	v_lshl_add_u64 v[34:35], s[82:83], 2, v[34:35]
	s_lshl_b32 s16, s88, 2
	v_lshl_add_u64 v[34:35], v[34:35], 0, s[16:17]
	global_store_dword v[34:35], v38, off
.LBB0_1100:
	s_or_b64 exec, exec, s[0:1]
	v_lshl_add_u64 v[44:45], s[52:53], 0, v[32:33]
	v_add_u32_e32 v32, 0x58000, v158
	v_add_u32_e32 v42, 0x58100, v158
	s_waitcnt lgkmcnt(0)
	v_mov_b32_e32 v59, v33
	s_waitcnt vmcnt(20)
	v_lshlrev_b32_e32 v48, 16, v214
	v_and_b32_e32 v49, 0xffff0000, v214
	v_lshl_add_u64 v[46:47], s[52:53], 0, v[58:59]
	v_lshlrev_b32_e32 v54, 16, v215
	v_and_b32_e32 v55, 0xffff0000, v215
	v_lshlrev_b32_e32 v58, 16, v216
	v_and_b32_e32 v59, 0xffff0000, v216
	v_lshlrev_b32_e32 v56, 16, v217
	v_and_b32_e32 v57, 0xffff0000, v217
	v_pk_add_f32 v[28:29], v[28:29], v[48:49]
	v_pk_add_f32 v[30:31], v[30:31], v[54:55]
	v_pk_add_f32 v[48:49], v[26:27], v[56:57]
	v_pk_add_f32 v[26:27], v[24:25], v[58:59]
	v_cvt_pk_bf16_f32 v24, v28, v29
	v_mul_f32_e32 v29, v29, v29
	v_fmac_f32_e32 v29, v28, v28
	v_mul_f32_e32 v28, v31, v31
	v_fmac_f32_e32 v28, v30, v30
	v_add_f32_e32 v28, v29, v28
	v_mul_f32_e32 v29, v27, v27
	v_fmac_f32_e32 v29, v26, v26
	v_add_f32_e32 v28, v29, v28
	v_mul_f32_e32 v29, v49, v49
	v_fmac_f32_e32 v29, v48, v48
	v_cvt_pk_bf16_f32 v25, v30, v31
	v_add_f32_e32 v43, v29, v28
	v_lshlrev_b32_e32 v28, 16, v218
	v_and_b32_e32 v29, 0xffff0000, v218
	v_lshlrev_b32_e32 v30, 16, v219
	v_and_b32_e32 v31, 0xffff0000, v219
	v_lshlrev_b32_e32 v50, 16, v220
	v_and_b32_e32 v51, 0xffff0000, v220
	v_pk_add_f32 v[22:23], v[22:23], v[30:31]
	v_pk_add_f32 v[20:21], v[20:21], v[28:29]
	v_pk_add_f32 v[30:31], v[16:17], v[50:51]
	v_mul_f32_e32 v16, v21, v21
	v_mul_f32_e32 v17, v23, v23
	v_fmac_f32_e32 v16, v20, v20
	v_fmac_f32_e32 v17, v22, v22
	v_lshlrev_b32_e32 v52, 16, v221
	v_and_b32_e32 v53, 0xffff0000, v221
	v_add_f32_e32 v16, v16, v17
	v_mul_f32_e32 v17, v31, v31
	v_pk_add_f32 v[28:29], v[18:19], v[52:53]
	v_fmac_f32_e32 v17, v30, v30
	v_add_f32_e32 v16, v17, v16
	v_mul_f32_e32 v17, v29, v29
	v_fmac_f32_e32 v17, v28, v28
	v_add_f32_e32 v16, v17, v16
	v_add_f32_e32 v16, v43, v16
	v_mov_b32_e32 v17, v16
	s_nop 1
	v_permlane16_swap_b32 v17, v16
	v_cvt_pk_bf16_f32 v26, v26, v27
	v_cvt_pk_bf16_f32 v27, v48, v49
	global_store_dwordx4 v[44:45], v[24:27], off
	v_cvt_pk_bf16_f32 v18, v20, v21
	s_waitcnt lgkmcnt(0)
	v_add_f32_e32 v16, v16, v17
	v_mov_b32_e32 v17, v16
	s_nop 1
	v_permlane32_swap_b32 v17, v16
	v_cvt_pk_bf16_f32 v19, v22, v23
	v_cvt_pk_bf16_f32 v20, v30, v31
	v_cvt_pk_bf16_f32 v21, v28, v29
	global_store_dwordx4 v[46:47], v[18:21], off
	s_and_saveexec_b64 s[0:1], vcc
	s_cbranch_execz .LBB0_1102
	v_add_u32_e32 v18, 0xa0, v150
	v_ashrrev_i32_e32 v19, 31, v18
	s_waitcnt lgkmcnt(0)
	v_add_f32_e32 v20, v16, v17
	v_lshlrev_b64 v[16:17], 6, v[18:19]
	v_lshl_add_u64 v[16:17], s[54:55], 0, v[16:17]
	v_lshl_add_u64 v[16:17], s[82:83], 2, v[16:17]
	s_lshl_b32 s16, s88, 2
	v_lshl_add_u64 v[16:17], v[16:17], 0, s[16:17]
	global_store_dword v[16:17], v20, off
.LBB0_1102:
	s_or_b64 exec, exec, s[0:1]
	s_waitcnt vmcnt(15)
	v_lshlrev_b32_e32 v20, 16, v134
	v_and_b32_e32 v21, 0xffff0000, v134
	v_lshlrev_b32_e32 v22, 16, v135
	v_and_b32_e32 v23, 0xffff0000, v135
	v_lshlrev_b32_e32 v24, 16, v136
	v_and_b32_e32 v25, 0xffff0000, v136
	v_lshlrev_b32_e32 v26, 16, v137
	v_and_b32_e32 v27, 0xffff0000, v137
	v_pk_add_f32 v[12:13], v[12:13], v[20:21]
	v_pk_add_f32 v[14:15], v[14:15], v[22:23]
	v_pk_add_f32 v[20:21], v[10:11], v[26:27]
	v_pk_add_f32 v[10:11], v[8:9], v[24:25]
	v_cvt_pk_bf16_f32 v8, v12, v13
	v_mul_f32_e32 v13, v13, v13
	v_fmac_f32_e32 v13, v12, v12
	v_mul_f32_e32 v12, v15, v15
	v_fmac_f32_e32 v12, v14, v14
	v_add_f32_e32 v12, v13, v12
	v_mul_f32_e32 v13, v11, v11
	v_fmac_f32_e32 v13, v10, v10
	v_add_f32_e32 v12, v13, v12
	v_mul_f32_e32 v13, v21, v21
	v_fmac_f32_e32 v13, v20, v20
	v_cvt_pk_bf16_f32 v9, v14, v15
	v_add_f32_e32 v26, v13, v12
	v_lshlrev_b32_e32 v12, 16, v130
	v_and_b32_e32 v13, 0xffff0000, v130
	v_lshlrev_b32_e32 v14, 16, v131
	v_and_b32_e32 v15, 0xffff0000, v131
	v_lshlrev_b32_e32 v22, 16, v132
	v_and_b32_e32 v23, 0xffff0000, v132
	v_pk_add_f32 v[6:7], v[6:7], v[14:15]
	v_pk_add_f32 v[4:5], v[4:5], v[12:13]
	v_pk_add_f32 v[14:15], v[0:1], v[22:23]
	v_mul_f32_e32 v0, v5, v5
	v_mul_f32_e32 v1, v7, v7
	v_fmac_f32_e32 v0, v4, v4
	v_fmac_f32_e32 v1, v6, v6
	v_lshlrev_b32_e32 v24, 16, v133
	v_and_b32_e32 v25, 0xffff0000, v133
	v_add_f32_e32 v0, v0, v1
	v_mul_f32_e32 v1, v15, v15
	v_pk_add_f32 v[12:13], v[2:3], v[24:25]
	v_fmac_f32_e32 v1, v14, v14
	v_add_f32_e32 v0, v1, v0
	v_mul_f32_e32 v1, v13, v13
	v_fmac_f32_e32 v1, v12, v12
	v_add_f32_e32 v0, v1, v0
	v_add_f32_e32 v0, v26, v0
	v_mov_b32_e32 v1, v0
	s_nop 1
	v_permlane16_swap_b32 v1, v0
	v_mov_b32_e32 v43, v33
	s_waitcnt lgkmcnt(1)
	v_lshl_add_u64 v[16:17], s[52:53], 0, v[32:33]
	v_lshl_add_u64 v[18:19], s[52:53], 0, v[42:43]
	v_cvt_pk_bf16_f32 v10, v10, v11
	s_waitcnt lgkmcnt(0)
	v_add_f32_e32 v0, v0, v1
	v_mov_b32_e32 v1, v0
	s_nop 1
	v_permlane32_swap_b32 v1, v0
	v_cvt_pk_bf16_f32 v11, v20, v21
	global_store_dwordx4 v[16:17], v[8:11], off
	v_cvt_pk_bf16_f32 v2, v4, v5
	v_cvt_pk_bf16_f32 v3, v6, v7
	v_cvt_pk_bf16_f32 v4, v14, v15
	v_cvt_pk_bf16_f32 v5, v12, v13
	global_store_dwordx4 v[18:19], v[2:5], off
	s_and_saveexec_b64 s[0:1], vcc
	s_cbranch_execz .LBB0_1104
	v_add_u32_e32 v2, 0xb0, v150
	v_ashrrev_i32_e32 v3, 31, v2
	s_waitcnt lgkmcnt(0)
	v_add_f32_e32 v4, v0, v1
	v_lshlrev_b64 v[0:1], 6, v[2:3]
	v_lshl_add_u64 v[0:1], s[54:55], 0, v[0:1]
	v_lshl_add_u64 v[0:1], s[82:83], 2, v[0:1]
	s_lshl_b32 s16, s88, 2
	v_lshl_add_u64 v[0:1], v[0:1], 0, s[16:17]
	global_store_dword v[0:1], v4, off

.LBB0_1272:
	s_lshl_b32 s0, s5, 8
	v_mov_b32_e32 v32, v155
	v_mov_b32_e32 v130, v154
	s_add_i32 s0, s0, s87
	s_lshl_b32 s70, s4, 2
	v_add_u32_e32 v150, s0, v32
	s_lshl_b32 s0, s4, 9
	s_or_b32 s0, s0, s88
	v_lshlrev_b32_e32 v32, 11, v150
	v_lshlrev_b32_e32 v131, 4, v130
	v_add3_u32 v158, s0, v131, v32
	global_load_dwordx4 v[160:163], v158, s[42:43]
	v_add_u32_e32 v151, 0x100, v158
	global_load_dwordx4 v[164:167], v151, s[42:43]
	v_add_u32_e32 v32, 0x8000, v158
	v_add_u32_e32 v152, 0x8100, v158
	v_cmp_eq_u32_e32 vcc, 0, v130
	global_load_dwordx4 v[134:137], v32, s[42:43]
	global_load_dwordx4 v[130:133], v152, s[42:43]
	v_add_u32_e32 v168, 0x10000, v158
	global_load_dwordx4 v[172:175], v168, s[42:43]
	v_add_u32_e32 v169, 0x10100, v158
	global_load_dwordx4 v[176:179], v169, s[42:43]
	v_add_u32_e32 v168, 0x18000, v158
	global_load_dwordx4 v[180:183], v168, s[42:43]
	v_add_u32_e32 v169, 0x18100, v158
	global_load_dwordx4 v[186:189], v169, s[42:43]
	v_add_u32_e32 v168, 0x40000, v158
	global_load_dwordx4 v[190:193], v168, s[42:43]
	v_add_u32_e32 v169, 0x40100, v158
	global_load_dwordx4 v[202:205], v169, s[42:43]
	v_add_u32_e32 v168, 0x48000, v158
	global_load_dwordx4 v[206:209], v168, s[42:43]
	v_add_u32_e32 v169, 0x48100, v158
	global_load_dwordx4 v[210:213], v169, s[42:43]
	v_add_u32_e32 v168, 0x50000, v158
	global_load_dwordx4 v[214:217], v168, s[42:43]
	v_add_u32_e32 v169, 0x50100, v158
	global_load_dwordx4 v[218:221], v169, s[42:43]
	s_ashr_i32 s71, s70, 31
	s_waitcnt vmcnt(12)
	v_lshlrev_b32_e32 v168, 16, v160
	v_and_b32_e32 v169, 0xffff0000, v160
	v_lshlrev_b32_e32 v160, 16, v161
	v_and_b32_e32 v161, 0xffff0000, v161
	v_lshlrev_b32_e32 v170, 16, v162
	v_and_b32_e32 v171, 0xffff0000, v162
	v_lshlrev_b32_e32 v162, 16, v163
	v_and_b32_e32 v163, 0xffff0000, v163
	v_pk_add_f32 v[128:129], v[128:129], v[160:161]
	v_pk_add_f32 v[126:127], v[126:127], v[168:169]
	v_pk_add_f32 v[160:161], v[124:125], v[162:163]
	v_pk_add_f32 v[162:163], v[122:123], v[170:171]
	v_cvt_pk_bf16_f32 v122, v126, v127
	v_cvt_pk_bf16_f32 v123, v128, v129
	s_nop 0
	v_cvt_pk_bf16_f32 v124, v162, v163
	v_cvt_pk_bf16_f32 v125, v160, v161
	global_store_dwordx4 v158, v[122:125], s[42:43]
	s_nop 1
	v_mul_f32_e32 v122, v127, v127
	v_mul_f32_e32 v123, v129, v129
	v_fmac_f32_e32 v122, v126, v126
	v_fmac_f32_e32 v123, v128, v128
	v_add_f32_e32 v122, v122, v123
	v_mul_f32_e32 v123, v163, v163
	v_fmac_f32_e32 v123, v162, v162
	v_add_f32_e32 v122, v123, v122
	v_mul_f32_e32 v123, v161, v161
	v_fmac_f32_e32 v123, v160, v160
	v_add_f32_e32 v153, v123, v122
	v_lshlrev_b32_e32 v122, 16, v164
	v_and_b32_e32 v123, 0xffff0000, v164
	v_lshlrev_b32_e32 v124, 16, v165
	v_and_b32_e32 v125, 0xffff0000, v165
	v_lshlrev_b32_e32 v126, 16, v166
	v_and_b32_e32 v127, 0xffff0000, v166
	v_lshlrev_b32_e32 v128, 16, v167
	v_and_b32_e32 v129, 0xffff0000, v167
	v_pk_add_f32 v[120:121], v[120:121], v[124:125]
	v_pk_add_f32 v[118:119], v[118:119], v[122:123]
	v_pk_add_f32 v[124:125], v[114:115], v[126:127]
	v_cvt_pk_bf16_f32 v114, v118, v119
	v_cvt_pk_bf16_f32 v115, v120, v121
	v_pk_add_f32 v[122:123], v[116:117], v[128:129]
	v_cvt_pk_bf16_f32 v116, v124, v125
	s_nop 0
	v_cvt_pk_bf16_f32 v117, v122, v123
	global_store_dwordx4 v151, v[114:117], s[42:43]
	s_nop 1
	v_mul_f32_e32 v114, v119, v119
	v_mul_f32_e32 v115, v121, v121
	v_fmac_f32_e32 v114, v118, v118
	v_fmac_f32_e32 v115, v120, v120
	v_add_f32_e32 v114, v114, v115
	v_mul_f32_e32 v115, v125, v125
	v_fmac_f32_e32 v115, v124, v124
	v_add_f32_e32 v114, v115, v114
	v_mul_f32_e32 v115, v123, v123
	v_fmac_f32_e32 v115, v122, v122
	v_and_b32_e32 v116, 64, v238
	v_add_f32_e32 v114, v115, v114
	v_xor_b32_e32 v115, 16, v238
	v_add_u32_e32 v116, 64, v116
	v_cmp_lt_i32_e64 s[0:1], v115, v116
	v_add_f32_e32 v114, v153, v114
	s_nop 0
	v_cndmask_b32_e64 v115, v238, v115, s[0:1]
	v_lshlrev_b32_e32 v124, 2, v115
	v_mov_b32_e32 v115, v114
	s_nop 1
	v_permlane16_swap_b32 v115, v114
	s_waitcnt lgkmcnt(0)
	v_add_f32_e32 v114, v114, v115
	v_xor_b32_e32 v115, 32, v238
	v_cmp_lt_i32_e64 s[0:1], v115, v116
	s_nop 1
	v_cndmask_b32_e64 v115, v238, v115, s[0:1]
	v_lshlrev_b32_e32 v125, 2, v115
	v_mov_b32_e32 v115, v114
	s_nop 1
	v_permlane32_swap_b32 v115, v114
	s_and_saveexec_b64 s[0:1], vcc
	s_cbranch_execz .LBB0_1274
	v_ashrrev_i32_e32 v151, 31, v150
	s_waitcnt lgkmcnt(0)
	v_add_f32_e32 v116, v114, v115
	v_lshlrev_b64 v[114:115], 6, v[150:151]
	v_lshl_add_u64 v[114:115], s[44:45], 0, v[114:115]
	v_lshl_add_u64 v[114:115], s[70:71], 2, v[114:115]
	s_lshl_b32 s16, s86, 2
	v_lshl_add_u64 v[114:115], v[114:115], 0, s[16:17]
	global_store_dword v[114:115], v116, off
.LBB0_1274:
	s_or_b64 exec, exec, s[0:1]
	v_lshl_add_u64 v[126:127], s[42:43], 0, v[32:33]
	v_add_u32_e32 v32, 0x10000, v158
	v_add_u32_e32 v122, 0x10100, v158
	s_waitcnt vmcnt(13)
	s_waitcnt lgkmcnt(0)
	v_mov_b32_e32 v153, v33
	v_lshl_add_u64 v[128:129], s[42:43], 0, v[152:153]
	v_lshlrev_b32_e32 v152, 16, v134
	v_and_b32_e32 v153, 0xffff0000, v134
	v_lshlrev_b32_e32 v134, 16, v135
	v_and_b32_e32 v135, 0xffff0000, v135
	v_lshlrev_b32_e32 v160, 16, v136
	v_and_b32_e32 v161, 0xffff0000, v136
	v_lshlrev_b32_e32 v136, 16, v137
	v_and_b32_e32 v137, 0xffff0000, v137
	v_pk_add_f32 v[110:111], v[110:111], v[152:153]
	v_pk_add_f32 v[112:113], v[112:113], v[134:135]
	v_pk_add_f32 v[134:135], v[108:109], v[136:137]
	v_pk_add_f32 v[108:109], v[106:107], v[160:161]
	v_cvt_pk_bf16_f32 v106, v110, v111
	v_mul_f32_e32 v111, v111, v111
	v_fmac_f32_e32 v111, v110, v110
	v_mul_f32_e32 v110, v113, v113
	v_fmac_f32_e32 v110, v112, v112
	v_add_f32_e32 v110, v111, v110
	v_mul_f32_e32 v111, v109, v109
	v_fmac_f32_e32 v111, v108, v108
	v_add_f32_e32 v110, v111, v110
	v_mul_f32_e32 v111, v135, v135
	v_fmac_f32_e32 v111, v134, v134
	v_cvt_pk_bf16_f32 v107, v112, v113
	v_add_f32_e32 v123, v111, v110
	v_lshlrev_b32_e32 v110, 16, v130
	v_and_b32_e32 v111, 0xffff0000, v130
	v_lshlrev_b32_e32 v112, 16, v131
	v_and_b32_e32 v113, 0xffff0000, v131
	v_lshlrev_b32_e32 v130, 16, v132
	v_and_b32_e32 v131, 0xffff0000, v132
	v_pk_add_f32 v[104:105], v[104:105], v[112:113]
	v_pk_add_f32 v[102:103], v[102:103], v[110:111]
	v_pk_add_f32 v[112:113], v[98:99], v[130:131]
	v_mul_f32_e32 v98, v103, v103
	v_mul_f32_e32 v99, v105, v105
	v_fmac_f32_e32 v98, v102, v102
	v_fmac_f32_e32 v99, v104, v104
	v_lshlrev_b32_e32 v132, 16, v133
	v_and_b32_e32 v133, 0xffff0000, v133
	v_add_f32_e32 v98, v98, v99
	v_mul_f32_e32 v99, v113, v113
	v_pk_add_f32 v[110:111], v[100:101], v[132:133]
	v_fmac_f32_e32 v99, v112, v112
	v_add_f32_e32 v98, v99, v98
	v_mul_f32_e32 v99, v111, v111
	v_fmac_f32_e32 v99, v110, v110
	v_add_f32_e32 v98, v99, v98
	v_add_f32_e32 v98, v123, v98
	v_mov_b32_e32 v99, v98
	s_nop 1
	v_permlane16_swap_b32 v99, v98
	v_cvt_pk_bf16_f32 v108, v108, v109
	v_cvt_pk_bf16_f32 v109, v134, v135
	global_store_dwordx4 v[126:127], v[106:109], off
	v_cvt_pk_bf16_f32 v100, v102, v103
	s_waitcnt lgkmcnt(0)
	v_add_f32_e32 v98, v98, v99
	v_mov_b32_e32 v99, v98
	s_nop 1
	v_permlane32_swap_b32 v99, v98
	v_cvt_pk_bf16_f32 v101, v104, v105
	v_cvt_pk_bf16_f32 v102, v112, v113
	v_cvt_pk_bf16_f32 v103, v110, v111
	global_store_dwordx4 v[128:129], v[100:103], off
	s_and_saveexec_b64 s[0:1], vcc
	s_cbranch_execz .LBB0_1276
	v_add_u32_e32 v100, 16, v150
	v_ashrrev_i32_e32 v101, 31, v100
	s_waitcnt lgkmcnt(0)
	v_add_f32_e32 v102, v98, v99
	v_lshlrev_b64 v[98:99], 6, v[100:101]
	v_lshl_add_u64 v[98:99], s[44:45], 0, v[98:99]
	v_lshl_add_u64 v[98:99], s[70:71], 2, v[98:99]
	s_lshl_b32 s16, s86, 2
	v_lshl_add_u64 v[98:99], v[98:99], 0, s[16:17]
	global_store_dword v[98:99], v102, off
.LBB0_1276:
	s_or_b64 exec, exec, s[0:1]
	v_lshl_add_u64 v[108:109], s[42:43], 0, v[32:33]
	v_add_u32_e32 v32, 0x18000, v158
	v_add_u32_e32 v106, 0x18100, v158
	v_add_u32_e32 v168, 0x58000, v158
	global_load_dwordx4 v[134:137], v168, s[42:43]
	v_add_u32_e32 v169, 0x58100, v158
	global_load_dwordx4 v[130:133], v169, s[42:43]
	s_waitcnt lgkmcnt(0)
	v_mov_b32_e32 v123, v33
	s_waitcnt vmcnt(16)
	v_lshlrev_b32_e32 v112, 16, v172
	v_and_b32_e32 v113, 0xffff0000, v172
	v_lshl_add_u64 v[110:111], s[42:43], 0, v[122:123]
	v_lshlrev_b32_e32 v118, 16, v173
	v_and_b32_e32 v119, 0xffff0000, v173
	v_lshlrev_b32_e32 v122, 16, v174
	v_and_b32_e32 v123, 0xffff0000, v174
	v_lshlrev_b32_e32 v120, 16, v175
	v_and_b32_e32 v121, 0xffff0000, v175
	v_pk_add_f32 v[94:95], v[94:95], v[112:113]
	v_pk_add_f32 v[96:97], v[96:97], v[118:119]
	v_pk_add_f32 v[112:113], v[92:93], v[120:121]
	v_pk_add_f32 v[92:93], v[90:91], v[122:123]
	v_cvt_pk_bf16_f32 v90, v94, v95
	v_mul_f32_e32 v95, v95, v95
	v_fmac_f32_e32 v95, v94, v94
	v_mul_f32_e32 v94, v97, v97
	v_fmac_f32_e32 v94, v96, v96
	v_add_f32_e32 v94, v95, v94
	v_mul_f32_e32 v95, v93, v93
	v_fmac_f32_e32 v95, v92, v92
	v_add_f32_e32 v94, v95, v94
	v_mul_f32_e32 v95, v113, v113
	v_fmac_f32_e32 v95, v112, v112
	v_cvt_pk_bf16_f32 v91, v96, v97
	v_add_f32_e32 v107, v95, v94
	v_lshlrev_b32_e32 v94, 16, v176
	v_and_b32_e32 v95, 0xffff0000, v176
	v_lshlrev_b32_e32 v96, 16, v177
	v_and_b32_e32 v97, 0xffff0000, v177
	v_lshlrev_b32_e32 v114, 16, v178
	v_and_b32_e32 v115, 0xffff0000, v178
	v_pk_add_f32 v[88:89], v[88:89], v[96:97]
	v_pk_add_f32 v[86:87], v[86:87], v[94:95]
	v_pk_add_f32 v[96:97], v[82:83], v[114:115]
	v_mul_f32_e32 v82, v87, v87
	v_mul_f32_e32 v83, v89, v89
	v_fmac_f32_e32 v82, v86, v86
	v_fmac_f32_e32 v83, v88, v88
	v_lshlrev_b32_e32 v116, 16, v179
	v_and_b32_e32 v117, 0xffff0000, v179
	v_add_f32_e32 v82, v82, v83
	v_mul_f32_e32 v83, v97, v97
	v_pk_add_f32 v[94:95], v[84:85], v[116:117]
	v_fmac_f32_e32 v83, v96, v96
	v_add_f32_e32 v82, v83, v82
	v_mul_f32_e32 v83, v95, v95
	v_fmac_f32_e32 v83, v94, v94
	v_add_f32_e32 v82, v83, v82
	v_add_f32_e32 v82, v107, v82
	v_mov_b32_e32 v83, v82
	s_nop 1
	v_permlane16_swap_b32 v83, v82
	v_cvt_pk_bf16_f32 v92, v92, v93
	v_cvt_pk_bf16_f32 v93, v112, v113
	global_store_dwordx4 v[108:109], v[90:93], off
	v_cvt_pk_bf16_f32 v84, v86, v87
	s_waitcnt lgkmcnt(0)
	v_add_f32_e32 v82, v82, v83
	v_mov_b32_e32 v83, v82
	s_nop 1
	v_permlane32_swap_b32 v83, v82
	v_cvt_pk_bf16_f32 v85, v88, v89
	v_cvt_pk_bf16_f32 v86, v96, v97
	v_cvt_pk_bf16_f32 v87, v94, v95
	global_store_dwordx4 v[110:111], v[84:87], off
	s_and_saveexec_b64 s[0:1], vcc
	s_cbranch_execz .LBB0_1278
	v_add_u32_e32 v84, 32, v150
	v_ashrrev_i32_e32 v85, 31, v84
	s_waitcnt lgkmcnt(0)
	v_add_f32_e32 v86, v82, v83
	v_lshlrev_b64 v[82:83], 6, v[84:85]
	v_lshl_add_u64 v[82:83], s[44:45], 0, v[82:83]
	v_lshl_add_u64 v[82:83], s[70:71], 2, v[82:83]
	s_lshl_b32 s16, s86, 2
	v_lshl_add_u64 v[82:83], v[82:83], 0, s[16:17]
	global_store_dword v[82:83], v86, off
.LBB0_1278:
	s_or_b64 exec, exec, s[0:1]
	v_lshl_add_u64 v[92:93], s[42:43], 0, v[32:33]
	v_add_u32_e32 v32, 0x40000, v158
	v_add_u32_e32 v90, 0x40100, v158
	s_waitcnt lgkmcnt(0)
	v_mov_b32_e32 v107, v33
	s_waitcnt vmcnt(17)
	v_lshlrev_b32_e32 v96, 16, v180
	v_and_b32_e32 v97, 0xffff0000, v180
	v_lshl_add_u64 v[94:95], s[42:43], 0, v[106:107]
	v_lshlrev_b32_e32 v102, 16, v181
	v_and_b32_e32 v103, 0xffff0000, v181
	v_lshlrev_b32_e32 v106, 16, v182
	v_and_b32_e32 v107, 0xffff0000, v182
	v_lshlrev_b32_e32 v104, 16, v183
	v_and_b32_e32 v105, 0xffff0000, v183
	v_pk_add_f32 v[78:79], v[78:79], v[96:97]
	v_pk_add_f32 v[80:81], v[80:81], v[102:103]
	v_pk_add_f32 v[96:97], v[76:77], v[104:105]
	v_pk_add_f32 v[76:77], v[74:75], v[106:107]
	v_cvt_pk_bf16_f32 v74, v78, v79
	v_mul_f32_e32 v79, v79, v79
	v_fmac_f32_e32 v79, v78, v78
	v_mul_f32_e32 v78, v81, v81
	v_fmac_f32_e32 v78, v80, v80
	v_add_f32_e32 v78, v79, v78
	v_mul_f32_e32 v79, v77, v77
	v_fmac_f32_e32 v79, v76, v76
	v_add_f32_e32 v78, v79, v78
	v_mul_f32_e32 v79, v97, v97
	v_fmac_f32_e32 v79, v96, v96
	v_cvt_pk_bf16_f32 v75, v80, v81
	v_add_f32_e32 v91, v79, v78
	v_lshlrev_b32_e32 v78, 16, v186
	v_and_b32_e32 v79, 0xffff0000, v186
	v_lshlrev_b32_e32 v80, 16, v187
	v_and_b32_e32 v81, 0xffff0000, v187
	v_lshlrev_b32_e32 v98, 16, v188
	v_and_b32_e32 v99, 0xffff0000, v188
	v_pk_add_f32 v[72:73], v[72:73], v[80:81]
	v_pk_add_f32 v[70:71], v[70:71], v[78:79]
	v_pk_add_f32 v[80:81], v[66:67], v[98:99]
	v_mul_f32_e32 v66, v71, v71
	v_mul_f32_e32 v67, v73, v73
	v_fmac_f32_e32 v66, v70, v70
	v_fmac_f32_e32 v67, v72, v72
	v_lshlrev_b32_e32 v100, 16, v189
	v_and_b32_e32 v101, 0xffff0000, v189
	v_add_f32_e32 v66, v66, v67
	v_mul_f32_e32 v67, v81, v81
	v_pk_add_f32 v[78:79], v[68:69], v[100:101]
	v_fmac_f32_e32 v67, v80, v80
	v_add_f32_e32 v66, v67, v66
	v_mul_f32_e32 v67, v79, v79
	v_fmac_f32_e32 v67, v78, v78
	v_add_f32_e32 v66, v67, v66
	v_add_f32_e32 v66, v91, v66
	v_mov_b32_e32 v67, v66
	s_nop 1
	v_permlane16_swap_b32 v67, v66
	v_cvt_pk_bf16_f32 v76, v76, v77
	v_cvt_pk_bf16_f32 v77, v96, v97
	global_store_dwordx4 v[92:93], v[74:77], off
	v_cvt_pk_bf16_f32 v68, v70, v71
	s_waitcnt lgkmcnt(0)
	v_add_f32_e32 v66, v66, v67
	v_mov_b32_e32 v67, v66
	s_nop 1
	v_permlane32_swap_b32 v67, v66
	v_cvt_pk_bf16_f32 v69, v72, v73
	v_cvt_pk_bf16_f32 v70, v80, v81
	v_cvt_pk_bf16_f32 v71, v78, v79
	global_store_dwordx4 v[94:95], v[68:71], off
	s_and_saveexec_b64 s[0:1], vcc
	s_cbranch_execz .LBB0_1280
	v_add_u32_e32 v68, 48, v150
	v_ashrrev_i32_e32 v69, 31, v68
	s_waitcnt lgkmcnt(0)
	v_add_f32_e32 v70, v66, v67
	v_lshlrev_b64 v[66:67], 6, v[68:69]
	v_lshl_add_u64 v[66:67], s[44:45], 0, v[66:67]
	v_lshl_add_u64 v[66:67], s[70:71], 2, v[66:67]
	s_lshl_b32 s16, s86, 2
	v_lshl_add_u64 v[66:67], v[66:67], 0, s[16:17]
	global_store_dword v[66:67], v70, off
.LBB0_1280:
	s_or_b64 exec, exec, s[0:1]
	v_lshl_add_u64 v[76:77], s[42:43], 0, v[32:33]
	v_add_u32_e32 v32, 0x48000, v158
	v_add_u32_e32 v74, 0x48100, v158
	s_waitcnt lgkmcnt(0)
	v_mov_b32_e32 v91, v33
	s_waitcnt vmcnt(18)
	v_lshlrev_b32_e32 v80, 16, v190
	v_and_b32_e32 v81, 0xffff0000, v190
	v_lshl_add_u64 v[78:79], s[42:43], 0, v[90:91]
	v_lshlrev_b32_e32 v86, 16, v191
	v_and_b32_e32 v87, 0xffff0000, v191
	v_lshlrev_b32_e32 v90, 16, v192
	v_and_b32_e32 v91, 0xffff0000, v192
	v_lshlrev_b32_e32 v88, 16, v193
	v_and_b32_e32 v89, 0xffff0000, v193
	v_pk_add_f32 v[62:63], v[62:63], v[80:81]
	v_pk_add_f32 v[64:65], v[64:65], v[86:87]
	v_pk_add_f32 v[80:81], v[60:61], v[88:89]
	v_pk_add_f32 v[60:61], v[58:59], v[90:91]
	v_cvt_pk_bf16_f32 v58, v62, v63
	v_mul_f32_e32 v63, v63, v63
	v_fmac_f32_e32 v63, v62, v62
	v_mul_f32_e32 v62, v65, v65
	v_fmac_f32_e32 v62, v64, v64
	v_add_f32_e32 v62, v63, v62
	v_mul_f32_e32 v63, v61, v61
	v_fmac_f32_e32 v63, v60, v60
	v_add_f32_e32 v62, v63, v62
	v_mul_f32_e32 v63, v81, v81
	v_fmac_f32_e32 v63, v80, v80
	v_cvt_pk_bf16_f32 v59, v64, v65
	v_add_f32_e32 v75, v63, v62
	v_lshlrev_b32_e32 v62, 16, v202
	v_and_b32_e32 v63, 0xffff0000, v202
	v_lshlrev_b32_e32 v64, 16, v203
	v_and_b32_e32 v65, 0xffff0000, v203
	v_lshlrev_b32_e32 v82, 16, v204
	v_and_b32_e32 v83, 0xffff0000, v204
	v_pk_add_f32 v[56:57], v[56:57], v[64:65]
	v_pk_add_f32 v[54:55], v[54:55], v[62:63]
	v_pk_add_f32 v[64:65], v[50:51], v[82:83]
	v_mul_f32_e32 v50, v55, v55
	v_mul_f32_e32 v51, v57, v57
	v_fmac_f32_e32 v50, v54, v54
	v_fmac_f32_e32 v51, v56, v56
	v_lshlrev_b32_e32 v84, 16, v205
	v_and_b32_e32 v85, 0xffff0000, v205
	v_add_f32_e32 v50, v50, v51
	v_mul_f32_e32 v51, v65, v65
	v_pk_add_f32 v[62:63], v[52:53], v[84:85]
	v_fmac_f32_e32 v51, v64, v64
	v_add_f32_e32 v50, v51, v50
	v_mul_f32_e32 v51, v63, v63
	v_fmac_f32_e32 v51, v62, v62
	v_add_f32_e32 v50, v51, v50
	v_add_f32_e32 v50, v75, v50
	v_mov_b32_e32 v51, v50
	s_nop 1
	v_permlane16_swap_b32 v51, v50
	v_cvt_pk_bf16_f32 v60, v60, v61
	v_cvt_pk_bf16_f32 v61, v80, v81
	global_store_dwordx4 v[76:77], v[58:61], off
	v_cvt_pk_bf16_f32 v52, v54, v55
	s_waitcnt lgkmcnt(0)
	v_add_f32_e32 v50, v50, v51
	v_mov_b32_e32 v51, v50
	s_nop 1
	v_permlane32_swap_b32 v51, v50
	v_cvt_pk_bf16_f32 v53, v56, v57
	v_cvt_pk_bf16_f32 v54, v64, v65
	v_cvt_pk_bf16_f32 v55, v62, v63
	global_store_dwordx4 v[78:79], v[52:55], off
	s_and_saveexec_b64 s[0:1], vcc
	s_cbranch_execz .LBB0_1282
	v_add_u32_e32 v52, 0x80, v150
	v_ashrrev_i32_e32 v53, 31, v52
	s_waitcnt lgkmcnt(0)
	v_add_f32_e32 v54, v50, v51
	v_lshlrev_b64 v[50:51], 6, v[52:53]
	v_lshl_add_u64 v[50:51], s[44:45], 0, v[50:51]
	v_lshl_add_u64 v[50:51], s[70:71], 2, v[50:51]
	s_lshl_b32 s16, s86, 2
	v_lshl_add_u64 v[50:51], v[50:51], 0, s[16:17]
	global_store_dword v[50:51], v54, off
.LBB0_1282:
	s_or_b64 exec, exec, s[0:1]
	v_lshl_add_u64 v[60:61], s[42:43], 0, v[32:33]
	v_add_u32_e32 v32, 0x50000, v158
	v_add_u32_e32 v58, 0x50100, v158
	s_waitcnt lgkmcnt(0)
	v_mov_b32_e32 v75, v33
	s_waitcnt vmcnt(19)
	v_lshlrev_b32_e32 v64, 16, v206
	v_and_b32_e32 v65, 0xffff0000, v206
	v_lshl_add_u64 v[62:63], s[42:43], 0, v[74:75]
	v_lshlrev_b32_e32 v70, 16, v207
	v_and_b32_e32 v71, 0xffff0000, v207
	v_lshlrev_b32_e32 v74, 16, v208
	v_and_b32_e32 v75, 0xffff0000, v208
	v_lshlrev_b32_e32 v72, 16, v209
	v_and_b32_e32 v73, 0xffff0000, v209
	v_pk_add_f32 v[46:47], v[46:47], v[64:65]
	v_pk_add_f32 v[48:49], v[48:49], v[70:71]
	v_pk_add_f32 v[64:65], v[44:45], v[72:73]
	v_pk_add_f32 v[44:45], v[42:43], v[74:75]
	v_cvt_pk_bf16_f32 v42, v46, v47
	v_mul_f32_e32 v47, v47, v47
	v_fmac_f32_e32 v47, v46, v46
	v_mul_f32_e32 v46, v49, v49
	v_fmac_f32_e32 v46, v48, v48
	v_add_f32_e32 v46, v47, v46
	v_mul_f32_e32 v47, v45, v45
	v_fmac_f32_e32 v47, v44, v44
	v_add_f32_e32 v46, v47, v46
	v_mul_f32_e32 v47, v65, v65
	v_fmac_f32_e32 v47, v64, v64
	v_cvt_pk_bf16_f32 v43, v48, v49
	v_add_f32_e32 v59, v47, v46
	v_lshlrev_b32_e32 v46, 16, v210
	v_and_b32_e32 v47, 0xffff0000, v210
	v_lshlrev_b32_e32 v48, 16, v211
	v_and_b32_e32 v49, 0xffff0000, v211
	v_lshlrev_b32_e32 v66, 16, v212
	v_and_b32_e32 v67, 0xffff0000, v212
	v_pk_add_f32 v[40:41], v[40:41], v[48:49]
	v_pk_add_f32 v[38:39], v[38:39], v[46:47]
	v_pk_add_f32 v[48:49], v[34:35], v[66:67]
	v_mul_f32_e32 v34, v39, v39
	v_mul_f32_e32 v35, v41, v41
	v_fmac_f32_e32 v34, v38, v38
	v_fmac_f32_e32 v35, v40, v40
	v_lshlrev_b32_e32 v68, 16, v213
	v_and_b32_e32 v69, 0xffff0000, v213
	v_add_f32_e32 v34, v34, v35
	v_mul_f32_e32 v35, v49, v49
	v_pk_add_f32 v[46:47], v[36:37], v[68:69]
	v_fmac_f32_e32 v35, v48, v48
	v_add_f32_e32 v34, v35, v34
	v_mul_f32_e32 v35, v47, v47
	v_fmac_f32_e32 v35, v46, v46
	v_add_f32_e32 v34, v35, v34
	v_add_f32_e32 v34, v59, v34
	v_mov_b32_e32 v35, v34
	s_nop 1
	v_permlane16_swap_b32 v35, v34
	v_cvt_pk_bf16_f32 v44, v44, v45
	v_cvt_pk_bf16_f32 v45, v64, v65
	global_store_dwordx4 v[60:61], v[42:45], off
	v_cvt_pk_bf16_f32 v36, v38, v39
	s_waitcnt lgkmcnt(0)
	v_add_f32_e32 v34, v34, v35
	v_mov_b32_e32 v35, v34
	s_nop 1
	v_permlane32_swap_b32 v35, v34
	v_cvt_pk_bf16_f32 v37, v40, v41
	v_cvt_pk_bf16_f32 v38, v48, v49
	v_cvt_pk_bf16_f32 v39, v46, v47
	global_store_dwordx4 v[62:63], v[36:39], off
	s_and_saveexec_b64 s[0:1], vcc
	s_cbranch_execz .LBB0_1284
	v_add_u32_e32 v36, 0x90, v150
	v_ashrrev_i32_e32 v37, 31, v36
	s_waitcnt lgkmcnt(0)
	v_add_f32_e32 v38, v34, v35
	v_lshlrev_b64 v[34:35], 6, v[36:37]
	v_lshl_add_u64 v[34:35], s[44:45], 0, v[34:35]
	v_lshl_add_u64 v[34:35], s[70:71], 2, v[34:35]
	s_lshl_b32 s16, s86, 2
	v_lshl_add_u64 v[34:35], v[34:35], 0, s[16:17]
	global_store_dword v[34:35], v38, off
.LBB0_1284:
	s_or_b64 exec, exec, s[0:1]
	v_lshl_add_u64 v[44:45], s[42:43], 0, v[32:33]
	v_add_u32_e32 v32, 0x58000, v158
	v_add_u32_e32 v42, 0x58100, v158
	s_waitcnt lgkmcnt(0)
	v_mov_b32_e32 v59, v33
	s_waitcnt vmcnt(20)
	v_lshlrev_b32_e32 v48, 16, v214
	v_and_b32_e32 v49, 0xffff0000, v214
	v_lshl_add_u64 v[46:47], s[42:43], 0, v[58:59]
	v_lshlrev_b32_e32 v54, 16, v215
	v_and_b32_e32 v55, 0xffff0000, v215
	v_lshlrev_b32_e32 v58, 16, v216
	v_and_b32_e32 v59, 0xffff0000, v216
	v_lshlrev_b32_e32 v56, 16, v217
	v_and_b32_e32 v57, 0xffff0000, v217
	v_pk_add_f32 v[28:29], v[28:29], v[48:49]
	v_pk_add_f32 v[30:31], v[30:31], v[54:55]
	v_pk_add_f32 v[48:49], v[26:27], v[56:57]
	v_pk_add_f32 v[26:27], v[24:25], v[58:59]
	v_cvt_pk_bf16_f32 v24, v28, v29
	v_mul_f32_e32 v29, v29, v29
	v_fmac_f32_e32 v29, v28, v28
	v_mul_f32_e32 v28, v31, v31
	v_fmac_f32_e32 v28, v30, v30
	v_add_f32_e32 v28, v29, v28
	v_mul_f32_e32 v29, v27, v27
	v_fmac_f32_e32 v29, v26, v26
	v_add_f32_e32 v28, v29, v28
	v_mul_f32_e32 v29, v49, v49
	v_fmac_f32_e32 v29, v48, v48
	v_cvt_pk_bf16_f32 v25, v30, v31
	v_add_f32_e32 v43, v29, v28
	v_lshlrev_b32_e32 v28, 16, v218
	v_and_b32_e32 v29, 0xffff0000, v218
	v_lshlrev_b32_e32 v30, 16, v219
	v_and_b32_e32 v31, 0xffff0000, v219
	v_lshlrev_b32_e32 v50, 16, v220
	v_and_b32_e32 v51, 0xffff0000, v220
	v_pk_add_f32 v[22:23], v[22:23], v[30:31]
	v_pk_add_f32 v[20:21], v[20:21], v[28:29]
	v_pk_add_f32 v[30:31], v[16:17], v[50:51]
	v_mul_f32_e32 v16, v21, v21
	v_mul_f32_e32 v17, v23, v23
	v_fmac_f32_e32 v16, v20, v20
	v_fmac_f32_e32 v17, v22, v22
	v_lshlrev_b32_e32 v52, 16, v221
	v_and_b32_e32 v53, 0xffff0000, v221
	v_add_f32_e32 v16, v16, v17
	v_mul_f32_e32 v17, v31, v31
	v_pk_add_f32 v[28:29], v[18:19], v[52:53]
	v_fmac_f32_e32 v17, v30, v30
	v_add_f32_e32 v16, v17, v16
	v_mul_f32_e32 v17, v29, v29
	v_fmac_f32_e32 v17, v28, v28
	v_add_f32_e32 v16, v17, v16
	v_add_f32_e32 v16, v43, v16
	v_mov_b32_e32 v17, v16
	s_nop 1
	v_permlane16_swap_b32 v17, v16
	v_cvt_pk_bf16_f32 v26, v26, v27
	v_cvt_pk_bf16_f32 v27, v48, v49
	global_store_dwordx4 v[44:45], v[24:27], off
	v_cvt_pk_bf16_f32 v18, v20, v21
	s_waitcnt lgkmcnt(0)
	v_add_f32_e32 v16, v16, v17
	v_mov_b32_e32 v17, v16
	s_nop 1
	v_permlane32_swap_b32 v17, v16
	v_cvt_pk_bf16_f32 v19, v22, v23
	v_cvt_pk_bf16_f32 v20, v30, v31
	v_cvt_pk_bf16_f32 v21, v28, v29
	global_store_dwordx4 v[46:47], v[18:21], off
	s_and_saveexec_b64 s[0:1], vcc
	s_cbranch_execz .LBB0_1286
	v_add_u32_e32 v18, 0xa0, v150
	v_ashrrev_i32_e32 v19, 31, v18
	s_waitcnt lgkmcnt(0)
	v_add_f32_e32 v20, v16, v17
	v_lshlrev_b64 v[16:17], 6, v[18:19]
	v_lshl_add_u64 v[16:17], s[44:45], 0, v[16:17]
	v_lshl_add_u64 v[16:17], s[70:71], 2, v[16:17]
	s_lshl_b32 s16, s86, 2
	v_lshl_add_u64 v[16:17], v[16:17], 0, s[16:17]
	global_store_dword v[16:17], v20, off
.LBB0_1286:
	s_or_b64 exec, exec, s[0:1]
	s_waitcnt vmcnt(15)
	v_lshlrev_b32_e32 v20, 16, v134
	v_and_b32_e32 v21, 0xffff0000, v134
	v_lshlrev_b32_e32 v22, 16, v135
	v_and_b32_e32 v23, 0xffff0000, v135
	v_lshlrev_b32_e32 v24, 16, v136
	v_and_b32_e32 v25, 0xffff0000, v136
	v_lshlrev_b32_e32 v26, 16, v137
	v_and_b32_e32 v27, 0xffff0000, v137
	v_pk_add_f32 v[12:13], v[12:13], v[20:21]
	v_pk_add_f32 v[14:15], v[14:15], v[22:23]
	v_pk_add_f32 v[20:21], v[10:11], v[26:27]
	v_pk_add_f32 v[10:11], v[8:9], v[24:25]
	v_cvt_pk_bf16_f32 v8, v12, v13
	v_mul_f32_e32 v13, v13, v13
	v_fmac_f32_e32 v13, v12, v12
	v_mul_f32_e32 v12, v15, v15
	v_fmac_f32_e32 v12, v14, v14
	v_add_f32_e32 v12, v13, v12
	v_mul_f32_e32 v13, v11, v11
	v_fmac_f32_e32 v13, v10, v10
	v_add_f32_e32 v12, v13, v12
	v_mul_f32_e32 v13, v21, v21
	v_fmac_f32_e32 v13, v20, v20
	v_cvt_pk_bf16_f32 v9, v14, v15
	v_add_f32_e32 v26, v13, v12
	v_lshlrev_b32_e32 v12, 16, v130
	v_and_b32_e32 v13, 0xffff0000, v130
	v_lshlrev_b32_e32 v14, 16, v131
	v_and_b32_e32 v15, 0xffff0000, v131
	v_lshlrev_b32_e32 v22, 16, v132
	v_and_b32_e32 v23, 0xffff0000, v132
	v_pk_add_f32 v[6:7], v[6:7], v[14:15]
	v_pk_add_f32 v[4:5], v[4:5], v[12:13]
	v_pk_add_f32 v[14:15], v[0:1], v[22:23]
	v_mul_f32_e32 v0, v5, v5
	v_mul_f32_e32 v1, v7, v7
	v_fmac_f32_e32 v0, v4, v4
	v_fmac_f32_e32 v1, v6, v6
	v_lshlrev_b32_e32 v24, 16, v133
	v_and_b32_e32 v25, 0xffff0000, v133
	v_add_f32_e32 v0, v0, v1
	v_mul_f32_e32 v1, v15, v15
	v_pk_add_f32 v[12:13], v[2:3], v[24:25]
	v_fmac_f32_e32 v1, v14, v14
	v_add_f32_e32 v0, v1, v0
	v_mul_f32_e32 v1, v13, v13
	v_fmac_f32_e32 v1, v12, v12
	v_add_f32_e32 v0, v1, v0
	v_add_f32_e32 v0, v26, v0
	v_mov_b32_e32 v1, v0
	s_nop 1
	v_permlane16_swap_b32 v1, v0
	v_mov_b32_e32 v43, v33
	s_waitcnt lgkmcnt(1)
	v_lshl_add_u64 v[16:17], s[42:43], 0, v[32:33]
	v_lshl_add_u64 v[18:19], s[42:43], 0, v[42:43]
	v_cvt_pk_bf16_f32 v10, v10, v11
	s_waitcnt lgkmcnt(0)
	v_add_f32_e32 v0, v0, v1
	v_mov_b32_e32 v1, v0
	s_nop 1
	v_permlane32_swap_b32 v1, v0
	v_cvt_pk_bf16_f32 v11, v20, v21
	global_store_dwordx4 v[16:17], v[8:11], off
	v_cvt_pk_bf16_f32 v2, v4, v5
	v_cvt_pk_bf16_f32 v3, v6, v7
	v_cvt_pk_bf16_f32 v4, v14, v15
	v_cvt_pk_bf16_f32 v5, v12, v13
	global_store_dwordx4 v[18:19], v[2:5], off
	s_and_saveexec_b64 s[0:1], vcc
	s_cbranch_execz .LBB0_1288
	v_add_u32_e32 v2, 0xb0, v150
	v_ashrrev_i32_e32 v3, 31, v2
	s_waitcnt lgkmcnt(0)
	v_add_f32_e32 v4, v0, v1
	v_lshlrev_b64 v[0:1], 6, v[2:3]
	v_lshl_add_u64 v[0:1], s[44:45], 0, v[0:1]
	v_lshl_add_u64 v[0:1], s[70:71], 2, v[0:1]
	s_lshl_b32 s16, s86, 2
	v_lshl_add_u64 v[0:1], v[0:1], 0, s[16:17]
	global_store_dword v[0:1], v4, off
